# GEMM1 K-loop: 64-bit VALU address adds folded into SGPR-base LDS-DMA requests (16 VALU ops per iteration removed)
# speedup vs baseline: 1.0101x; 1.0077x over previous
.LBB0_439:
	ds_read_b128 v[128:131], v192
	ds_read_b128 v[132:135], v192 offset:1024
	ds_read_b128 v[136:139], v192 offset:2048
	ds_read_b128 v[158:161], v192 offset:3072
	ds_read_b128 v[168:171], v193
	ds_read_b128 v[172:175], v193 offset:1024
	ds_read_b128 v[196:199], v193 offset:2048
	ds_read_b128 v[200:203], v193 offset:3072
	s_add_u32 s66, s64, 0xfffc0080
	s_addc_u32 s67, s65, -1
	s_cmp_eq_u32 s86, 12
	s_cselect_b32 s69, s53, s67
	s_cselect_b32 s68, s57, s66
	s_cselect_b32 s67, s55, s85
	s_cselect_b32 s66, s63, s84
	s_cselect_b32 s98, 1, 0
	s_add_i32 m0, s70, 0xc000
	ds_read_b128 v[204:207], v194
	ds_read_b128 v[208:211], v194 offset:1024
	ds_read_b128 v[212:215], v194 offset:2048
	ds_read_b128 v[216:219], v194 offset:3072
	ds_read_b128 v[220:223], v194 offset:4096
	ds_read_b128 v[224:227], v194 offset:5120
	ds_read_b128 v[228:231], v194 offset:6144
	ds_read_b128 v[232:235], v194 offset:7168
	global_load_lds_dwordx4 v150, s[64:65]
	s_add_i32 m0, s70, 0xe000
	s_nop 0
	global_load_lds_dwordx4 v152, s[64:65]
	s_waitcnt vmcnt(8)
	s_waitcnt lgkmcnt(0)
	s_setprio 1
	s_cmp_lg_u32 s98, 0
	s_cbranch_scc0 .Lg1_nopf
	s_lshl_b32 s99, s52, 8
	v_add_u32_e32 v240, s99, v165
	v_ashrrev_i32_e32 v241, 31, v240
	v_lshl_add_u64 v[240:241], v[240:241], 2, s[20:21]
	global_load_dword v242, v[240:241], off
	global_load_dword v243, v[240:241], off offset:64
	global_load_dword v244, v[240:241], off offset:128
	global_load_dword v245, v[240:241], off offset:192
	global_load_dword v246, v[240:241], off offset:512
	global_load_dword v248, v[240:241], off offset:576
	global_load_dword v249, v[240:241], off offset:640
	global_load_dword v250, v[240:241], off offset:704
.Lg1_nopf:
	s_barrier
	v_mfma_f32_16x16x32_bf16 v[124:127], v[128:131], v[204:207], v[124:127]
	v_mfma_f32_16x16x32_bf16 v[120:123], v[136:139], v[204:207], v[120:123]
	v_mfma_f32_16x16x32_bf16 v[96:99], v[128:131], v[212:215], v[96:99]
	v_mfma_f32_16x16x32_bf16 v[88:91], v[136:139], v[212:215], v[88:91]
	v_mfma_f32_16x16x32_bf16 v[76:79], v[128:131], v[220:223], v[76:79]
	v_mfma_f32_16x16x32_bf16 v[72:75], v[136:139], v[220:223], v[72:75]
	v_mfma_f32_16x16x32_bf16 v[60:63], v[128:131], v[228:231], v[60:63]
	v_mfma_f32_16x16x32_bf16 v[108:111], v[136:139], v[228:231], v[108:111]
	v_mfma_f32_16x16x32_bf16 v[124:127], v[132:135], v[208:211], v[124:127]
	v_mfma_f32_16x16x32_bf16 v[120:123], v[158:161], v[208:211], v[120:123]
	v_mfma_f32_16x16x32_bf16 v[96:99], v[132:135], v[216:219], v[96:99]
	v_mfma_f32_16x16x32_bf16 v[88:91], v[158:161], v[216:219], v[88:91]
	v_mfma_f32_16x16x32_bf16 v[76:79], v[132:135], v[224:227], v[76:79]
	v_mfma_f32_16x16x32_bf16 v[72:75], v[158:161], v[224:227], v[72:75]
	v_mfma_f32_16x16x32_bf16 v[60:63], v[132:135], v[232:235], v[60:63]
	v_mfma_f32_16x16x32_bf16 v[108:111], v[158:161], v[232:235], v[108:111]
	v_mfma_f32_16x16x32_bf16 v[116:119], v[168:171], v[204:207], v[116:119]
	v_mfma_f32_16x16x32_bf16 v[112:115], v[196:199], v[204:207], v[112:115]
	v_mfma_f32_16x16x32_bf16 v[84:87], v[168:171], v[212:215], v[84:87]
	v_mfma_f32_16x16x32_bf16 v[80:83], v[196:199], v[212:215], v[80:83]
	v_mfma_f32_16x16x32_bf16 v[68:71], v[168:171], v[220:223], v[68:71]
	v_mfma_f32_16x16x32_bf16 v[64:67], v[196:199], v[220:223], v[64:67]
	v_mfma_f32_16x16x32_bf16 v[104:107], v[168:171], v[228:231], v[104:107]
	v_mfma_f32_16x16x32_bf16 v[56:59], v[196:199], v[228:231], v[56:59]
	v_mfma_f32_16x16x32_bf16 v[116:119], v[172:175], v[208:211], v[116:119]
	v_mfma_f32_16x16x32_bf16 v[112:115], v[200:203], v[208:211], v[112:115]
	v_mfma_f32_16x16x32_bf16 v[84:87], v[172:175], v[216:219], v[84:87]
	v_mfma_f32_16x16x32_bf16 v[80:83], v[200:203], v[216:219], v[80:83]
	v_mfma_f32_16x16x32_bf16 v[68:71], v[172:175], v[224:227], v[68:71]
	v_mfma_f32_16x16x32_bf16 v[64:67], v[200:203], v[224:227], v[64:67]
	v_mfma_f32_16x16x32_bf16 v[104:107], v[172:175], v[232:235], v[104:107]
	v_mfma_f32_16x16x32_bf16 v[56:59], v[200:203], v[232:235], v[56:59]
	s_barrier
	s_setprio 0
	s_add_i32 s87, s82, s23
	s_add_u32 s98, s66, 0x80
	s_addc_u32 s99, s67, 0
	s_mov_b32 m0, s87
	ds_read_b128 v[204:207], v194 offset:16384
	ds_read_b128 v[208:211], v194 offset:17408
	ds_read_b128 v[212:215], v194 offset:18432
	ds_read_b128 v[216:219], v194 offset:19456
	ds_read_b128 v[220:223], v194 offset:20480
	ds_read_b128 v[224:227], v194 offset:21504
	ds_read_b128 v[228:231], v194 offset:22528
	ds_read_b128 v[232:235], v194 offset:23552
	global_load_lds_dwordx4 v140, s[66:67]
	s_add_i32 m0, s87, 0x2000
	s_add_u32 s88, s66, 0x40000
	s_addc_u32 s89, s67, 0
	s_add_i32 s87, s83, s23
	global_load_lds_dwordx4 v142, s[66:67]
	s_mov_b32 m0, s87
	s_add_u32 s100, s68, 0x80
	s_addc_u32 s101, s69, 0
	global_load_lds_dwordx4 v140, s[88:89]
	s_add_i32 m0, s87, 0x2000
	s_nop 0
	global_load_lds_dwordx4 v142, s[88:89]
	s_mov_b32 m0, s70
	s_nop 0
	global_load_lds_dwordx4 v140, s[68:69]
	s_mov_b32 m0, s71
	s_nop 0
	global_load_lds_dwordx4 v142, s[68:69]
	s_waitcnt vmcnt(8)
	s_waitcnt lgkmcnt(0)
	s_setprio 1
	s_barrier
	v_mfma_f32_16x16x32_bf16 v[52:55], v[128:131], v[204:207], v[52:55]
	v_mfma_f32_16x16x32_bf16 v[48:51], v[136:139], v[204:207], v[48:51]
	v_mfma_f32_16x16x32_bf16 v[16:19], v[128:131], v[212:215], v[16:19]
	v_mfma_f32_16x16x32_bf16 v[8:11], v[136:139], v[212:215], v[8:11]
	v_mfma_f32_16x16x32_bf16 v[28:31], v[128:131], v[220:223], v[28:31]
	v_mfma_f32_16x16x32_bf16 v[24:27], v[136:139], v[220:223], v[24:27]
	v_mfma_f32_16x16x32_bf16 v[36:39], v[128:131], v[228:231], v[36:39]
	v_mfma_f32_16x16x32_bf16 v[100:103], v[136:139], v[228:231], v[100:103]
	v_mfma_f32_16x16x32_bf16 v[52:55], v[132:135], v[208:211], v[52:55]
	v_mfma_f32_16x16x32_bf16 v[48:51], v[158:161], v[208:211], v[48:51]
	v_mfma_f32_16x16x32_bf16 v[16:19], v[132:135], v[216:219], v[16:19]
	v_mfma_f32_16x16x32_bf16 v[8:11], v[158:161], v[216:219], v[8:11]
	v_mfma_f32_16x16x32_bf16 v[28:31], v[132:135], v[224:227], v[28:31]
	v_mfma_f32_16x16x32_bf16 v[24:27], v[158:161], v[224:227], v[24:27]
	v_mfma_f32_16x16x32_bf16 v[36:39], v[132:135], v[232:235], v[36:39]
	v_mfma_f32_16x16x32_bf16 v[100:103], v[158:161], v[232:235], v[100:103]
	v_mfma_f32_16x16x32_bf16 v[44:47], v[168:171], v[204:207], v[44:47]
	v_mfma_f32_16x16x32_bf16 v[40:43], v[196:199], v[204:207], v[40:43]
	v_mfma_f32_16x16x32_bf16 v[0:3], v[168:171], v[212:215], v[0:3]
	v_mfma_f32_16x16x32_bf16 v[4:7], v[196:199], v[212:215], v[4:7]
	v_mfma_f32_16x16x32_bf16 v[12:15], v[168:171], v[220:223], v[12:15]
	v_mfma_f32_16x16x32_bf16 v[20:23], v[196:199], v[220:223], v[20:23]
	v_mfma_f32_16x16x32_bf16 v[92:95], v[168:171], v[228:231], v[92:95]
	v_mfma_f32_16x16x32_bf16 v[32:35], v[196:199], v[228:231], v[32:35]
	v_mfma_f32_16x16x32_bf16 v[44:47], v[172:175], v[208:211], v[44:47]
	v_mfma_f32_16x16x32_bf16 v[40:43], v[200:203], v[208:211], v[40:43]
	v_mfma_f32_16x16x32_bf16 v[0:3], v[172:175], v[216:219], v[0:3]
	v_mfma_f32_16x16x32_bf16 v[4:7], v[200:203], v[216:219], v[4:7]
	v_mfma_f32_16x16x32_bf16 v[12:15], v[172:175], v[224:227], v[12:15]
	v_mfma_f32_16x16x32_bf16 v[20:23], v[200:203], v[224:227], v[20:23]
	v_mfma_f32_16x16x32_bf16 v[92:95], v[172:175], v[232:235], v[92:95]
	v_mfma_f32_16x16x32_bf16 v[32:35], v[200:203], v[232:235], v[32:35]
	s_barrier
	s_setprio 0
	s_add_i32 s87, 0, 0x18000
	s_add_i32 s88, 0, 0x1c000
	v_add_u32_e32 v158, s87, v167
	v_add_u32_e32 v164, s88, v167
	ds_read_b128 v[128:131], v158
	ds_read_b128 v[132:135], v158 offset:1024
	ds_read_b128 v[136:139], v158 offset:2048
	ds_read_b128 v[158:161], v158 offset:3072
	ds_read_b128 v[168:171], v164
	ds_read_b128 v[172:175], v164 offset:1024
	ds_read_b128 v[196:199], v164 offset:2048
	ds_read_b128 v[200:203], v164 offset:3072
	s_add_u32 s68, s68, 0x40000
	s_addc_u32 s69, s69, 0
	s_mov_b32 m0, s72
	ds_read_b128 v[204:207], v194 offset:32768
	ds_read_b128 v[208:211], v194 offset:33792
	ds_read_b128 v[212:215], v194 offset:34816
	ds_read_b128 v[216:219], v194 offset:35840
	ds_read_b128 v[220:223], v194 offset:36864
	ds_read_b128 v[224:227], v194 offset:37888
	ds_read_b128 v[228:231], v194 offset:38912
	ds_read_b128 v[232:235], v194 offset:39936
	global_load_lds_dwordx4 v140, s[68:69]
	s_mov_b32 m0, s73
	s_nop 0
	global_load_lds_dwordx4 v142, s[68:69]
	s_waitcnt vmcnt(8)
	s_waitcnt lgkmcnt(0)
	s_setprio 1
	s_barrier
	v_mfma_f32_16x16x32_bf16 v[124:127], v[128:131], v[204:207], v[124:127]
	v_mfma_f32_16x16x32_bf16 v[120:123], v[136:139], v[204:207], v[120:123]
	v_mfma_f32_16x16x32_bf16 v[96:99], v[128:131], v[212:215], v[96:99]
	v_mfma_f32_16x16x32_bf16 v[88:91], v[136:139], v[212:215], v[88:91]
	v_mfma_f32_16x16x32_bf16 v[76:79], v[128:131], v[220:223], v[76:79]
	v_mfma_f32_16x16x32_bf16 v[72:75], v[136:139], v[220:223], v[72:75]
	v_mfma_f32_16x16x32_bf16 v[60:63], v[128:131], v[228:231], v[60:63]
	v_mfma_f32_16x16x32_bf16 v[108:111], v[136:139], v[228:231], v[108:111]
	v_mfma_f32_16x16x32_bf16 v[124:127], v[132:135], v[208:211], v[124:127]
	v_mfma_f32_16x16x32_bf16 v[120:123], v[158:161], v[208:211], v[120:123]
	v_mfma_f32_16x16x32_bf16 v[96:99], v[132:135], v[216:219], v[96:99]
	v_mfma_f32_16x16x32_bf16 v[88:91], v[158:161], v[216:219], v[88:91]
	v_mfma_f32_16x16x32_bf16 v[76:79], v[132:135], v[224:227], v[76:79]
	v_mfma_f32_16x16x32_bf16 v[72:75], v[158:161], v[224:227], v[72:75]
	v_mfma_f32_16x16x32_bf16 v[60:63], v[132:135], v[232:235], v[60:63]
	v_mfma_f32_16x16x32_bf16 v[108:111], v[158:161], v[232:235], v[108:111]
	v_mfma_f32_16x16x32_bf16 v[116:119], v[168:171], v[204:207], v[116:119]
	v_mfma_f32_16x16x32_bf16 v[112:115], v[196:199], v[204:207], v[112:115]
	v_mfma_f32_16x16x32_bf16 v[84:87], v[168:171], v[212:215], v[84:87]
	v_mfma_f32_16x16x32_bf16 v[80:83], v[196:199], v[212:215], v[80:83]
	v_mfma_f32_16x16x32_bf16 v[68:71], v[168:171], v[220:223], v[68:71]
	v_mfma_f32_16x16x32_bf16 v[64:67], v[196:199], v[220:223], v[64:67]
	v_mfma_f32_16x16x32_bf16 v[104:107], v[168:171], v[228:231], v[104:107]
	v_mfma_f32_16x16x32_bf16 v[56:59], v[196:199], v[228:231], v[56:59]
	v_mfma_f32_16x16x32_bf16 v[116:119], v[172:175], v[208:211], v[116:119]
	v_mfma_f32_16x16x32_bf16 v[112:115], v[200:203], v[208:211], v[112:115]
	v_mfma_f32_16x16x32_bf16 v[84:87], v[172:175], v[216:219], v[84:87]
	v_mfma_f32_16x16x32_bf16 v[80:83], v[200:203], v[216:219], v[80:83]
	v_mfma_f32_16x16x32_bf16 v[68:71], v[172:175], v[224:227], v[68:71]
	v_mfma_f32_16x16x32_bf16 v[64:67], v[200:203], v[224:227], v[64:67]
	v_mfma_f32_16x16x32_bf16 v[104:107], v[172:175], v[232:235], v[104:107]
	v_mfma_f32_16x16x32_bf16 v[56:59], v[200:203], v[232:235], v[56:59]
	s_barrier
	s_setprio 0
	s_add_i32 s68, s87, s23
	s_mov_b32 m0, s68
	ds_read_b128 v[204:207], v194 offset:49152
	ds_read_b128 v[208:211], v194 offset:50176
	ds_read_b128 v[212:215], v194 offset:51200
	ds_read_b128 v[216:219], v194 offset:52224
	ds_read_b128 v[220:223], v194 offset:53248
	ds_read_b128 v[224:227], v194 offset:54272
	ds_read_b128 v[228:231], v194 offset:55296
	ds_read_b128 v[232:235], v194 offset:56320
	global_load_lds_dwordx4 v140, s[98:99]
	s_add_i32 m0, s68, 0x2000
	s_add_u32 s66, s66, 0x40080
	s_addc_u32 s67, s67, 0
	s_add_i32 s68, s88, s23
	global_load_lds_dwordx4 v142, s[98:99]
	s_mov_b32 m0, s68
	s_nop 0
	global_load_lds_dwordx4 v140, s[66:67]
	s_add_i32 m0, s68, 0x2000
	s_nop 0
	global_load_lds_dwordx4 v142, s[66:67]
	s_mov_b32 m0, s80
	s_nop 0
	global_load_lds_dwordx4 v140, s[100:101]
	s_mov_b32 m0, s81
	s_nop 0
	global_load_lds_dwordx4 v142, s[100:101]
	s_waitcnt vmcnt(8)
	s_waitcnt lgkmcnt(0)
	s_setprio 1
	s_barrier
	v_mfma_f32_16x16x32_bf16 v[52:55], v[128:131], v[204:207], v[52:55]
	v_mfma_f32_16x16x32_bf16 v[48:51], v[136:139], v[204:207], v[48:51]
	v_mfma_f32_16x16x32_bf16 v[16:19], v[128:131], v[212:215], v[16:19]
	v_mfma_f32_16x16x32_bf16 v[8:11], v[136:139], v[212:215], v[8:11]
	v_mfma_f32_16x16x32_bf16 v[28:31], v[128:131], v[220:223], v[28:31]
	v_mfma_f32_16x16x32_bf16 v[24:27], v[136:139], v[220:223], v[24:27]
	v_mfma_f32_16x16x32_bf16 v[36:39], v[128:131], v[228:231], v[36:39]
	v_mfma_f32_16x16x32_bf16 v[100:103], v[136:139], v[228:231], v[100:103]
	v_mfma_f32_16x16x32_bf16 v[52:55], v[132:135], v[208:211], v[52:55]
	v_mfma_f32_16x16x32_bf16 v[48:51], v[158:161], v[208:211], v[48:51]
	v_mfma_f32_16x16x32_bf16 v[16:19], v[132:135], v[216:219], v[16:19]
	v_mfma_f32_16x16x32_bf16 v[8:11], v[158:161], v[216:219], v[8:11]
	v_mfma_f32_16x16x32_bf16 v[28:31], v[132:135], v[224:227], v[28:31]
	v_mfma_f32_16x16x32_bf16 v[24:27], v[158:161], v[224:227], v[24:27]
	v_mfma_f32_16x16x32_bf16 v[36:39], v[132:135], v[232:235], v[36:39]
	v_mfma_f32_16x16x32_bf16 v[100:103], v[158:161], v[232:235], v[100:103]
	v_mfma_f32_16x16x32_bf16 v[44:47], v[168:171], v[204:207], v[44:47]
	v_mfma_f32_16x16x32_bf16 v[40:43], v[196:199], v[204:207], v[40:43]
	v_mfma_f32_16x16x32_bf16 v[0:3], v[168:171], v[212:215], v[0:3]
	v_mfma_f32_16x16x32_bf16 v[4:7], v[196:199], v[212:215], v[4:7]
	v_mfma_f32_16x16x32_bf16 v[12:15], v[168:171], v[220:223], v[12:15]
	v_mfma_f32_16x16x32_bf16 v[20:23], v[196:199], v[220:223], v[20:23]
	v_mfma_f32_16x16x32_bf16 v[92:95], v[168:171], v[228:231], v[92:95]
	v_mfma_f32_16x16x32_bf16 v[32:35], v[196:199], v[228:231], v[32:35]
	v_mfma_f32_16x16x32_bf16 v[44:47], v[172:175], v[208:211], v[44:47]
	v_mfma_f32_16x16x32_bf16 v[40:43], v[200:203], v[208:211], v[40:43]
	v_mfma_f32_16x16x32_bf16 v[0:3], v[172:175], v[216:219], v[0:3]
	v_mfma_f32_16x16x32_bf16 v[4:7], v[200:203], v[216:219], v[4:7]
	v_mfma_f32_16x16x32_bf16 v[12:15], v[172:175], v[224:227], v[12:15]
	v_mfma_f32_16x16x32_bf16 v[20:23], v[200:203], v[224:227], v[20:23]
	v_mfma_f32_16x16x32_bf16 v[92:95], v[172:175], v[232:235], v[92:95]
	v_mfma_f32_16x16x32_bf16 v[32:35], v[200:203], v[232:235], v[32:35]
	s_barrier
	s_setprio 0
	s_add_i32 s86, s86, 2
	s_add_u32 s64, s64, 0x100
	s_addc_u32 s65, s65, 0
	s_add_u32 s84, s84, 0x100
	s_addc_u32 s85, s85, 0
	s_cmp_gt_u32 s86, 13
	s_cbranch_scc0 .LBB0_439
	s_and_b64 vcc, exec, s[38:39]
	s_cbranch_vccz .LBB0_442
	s_barrier
